# SwiGLU epilogue software-pipelined across the 8 groups: exp/rcp (trans) interleaved with the mul/add/cvt/permlane of neighbouring groups
# speedup vs baseline: 1.0061x; 1.0061x over previous
; DI unsigned pack2(float a, float b) { f32x2 v = {a, b}; return __builtin_bit_cast(unsigned, __builtin_convertvector(v, hwbf16x2)); }
; template <int EPI>
; DI void gemm8_epilogue(const GemmArgs& g, f32x4 (&acc)[2][2][4][2], const int brow, const int bcol, const int wr, const int wc, const int fr, const int fq) {
; #pragma unroll
;   for (int ai = 0; ai < 2; ++ai) {
; #pragma unroll
;     for (int bj = 0; bj < 2; ++bj) {
;       const int cb = bcol + bj * 128 + wc * 32;
;       const int r0 = brow + ai * 128 + wr * 64 + fr;
;       if constexpr (EPI == EPI_SWIGLU) {
;         bf16_t* H = (bf16_t*)g.out0;
;         const int hc = (cb >> 1) + fq * 4;
; #pragma unroll
;         for (int m = 0; m < 4; ++m) {
;           float v[4];
; #pragma unroll
;           for (int j = 0; j < 4; ++j) { const float gt = acc[ai][bj][m][0][j], up = acc[ai][bj][m][1][j]; v[j] = gt * up * __builtin_amdgcn_rcpf(1.f + __expf(-gt)); }
;           u32x2 o; o.x = pack2(v[0], v[1]); o.y = pack2(v[2], v[3]);
;           *(u32x2*)&H[(size_t)(r0 + m * 16) * DFF + hc] = o;
;         }
.LBB0_295:
	v_lshl_add_u32 v157, s20, 8, v138
	s_lshl_b32 s21, s21, 7
	s_add_i32 s21, s21, s68
	v_lshl_add_u32 v136, v140, 1, s21
	v_ashrrev_i32_e32 v137, 31, v136
	v_lshl_add_u64 v[136:137], v[136:137], 1, s[60:61]
	s_mov_b64 s[20:21], 0x16000
	s_mov_b64 s[34:35], 0x6e000
	v_mad_i64_i32 v[158:159], vcc, v157, s33, v[136:137]
	v_pk_mul_f32 v[126:127], v[122:123], v[126:127]
	v_pk_mul_f32 v[128:129], v[124:125], v[128:129]
	v_pk_mul_f32 v[94:95], v[90:91], v[94:95]
	v_pk_mul_f32 v[96:97], v[92:93], v[96:97]
	v_mul_f32_e32 v122, 0xbfb8aa3b, v122
	v_mul_f32_e32 v123, 0xbfb8aa3b, v123
	v_mul_f32_e32 v124, 0xbfb8aa3b, v124
	v_mul_f32_e32 v125, 0xbfb8aa3b, v125
	v_mul_f32_e32 v90, 0xbfb8aa3b, v90
	v_mul_f32_e32 v91, 0xbfb8aa3b, v91
	v_mul_f32_e32 v92, 0xbfb8aa3b, v92
	v_mul_f32_e32 v93, 0xbfb8aa3b, v93
	v_exp_f32_e32 v122, v122
	v_exp_f32_e32 v123, v123
	v_exp_f32_e32 v124, v124
	v_exp_f32_e32 v125, v125
	v_exp_f32_e32 v90, v90
	v_exp_f32_e32 v91, v91
	v_exp_f32_e32 v92, v92
	v_exp_f32_e32 v93, v93
	v_add_f32_e32 v122, 1.0, v122
	v_add_f32_e32 v123, 1.0, v123
	v_add_f32_e32 v124, 1.0, v124
	v_add_f32_e32 v125, 1.0, v125
	v_add_f32_e32 v90, 1.0, v90
	v_add_f32_e32 v91, 1.0, v91
	v_add_f32_e32 v92, 1.0, v92
	v_add_f32_e32 v93, 1.0, v93
	v_pk_mul_f32 v[118:119], v[114:115], v[118:119]
	v_pk_mul_f32 v[120:121], v[116:117], v[120:121]
	v_pk_mul_f32 v[86:87], v[82:83], v[86:87]
	v_pk_mul_f32 v[88:89], v[84:85], v[88:89]
	v_mul_f32_e32 v114, 0xbfb8aa3b, v114
	v_mul_f32_e32 v115, 0xbfb8aa3b, v115
	v_mul_f32_e32 v116, 0xbfb8aa3b, v116
	v_mul_f32_e32 v117, 0xbfb8aa3b, v117
	v_mul_f32_e32 v82, 0xbfb8aa3b, v82
	v_mul_f32_e32 v83, 0xbfb8aa3b, v83
	v_mul_f32_e32 v84, 0xbfb8aa3b, v84
	v_mul_f32_e32 v85, 0xbfb8aa3b, v85
	v_exp_f32_e32 v114, v114
	v_exp_f32_e32 v115, v115
	v_exp_f32_e32 v116, v116
	v_exp_f32_e32 v117, v117
	v_exp_f32_e32 v82, v82
	v_exp_f32_e32 v83, v83
	v_exp_f32_e32 v84, v84
	v_exp_f32_e32 v85, v85
	v_rcp_f32_e32 v122, v122
	v_add_f32_e32 v114, 1.0, v114
	v_add_f32_e32 v115, 1.0, v115
	v_add_f32_e32 v116, 1.0, v116
	v_rcp_f32_e32 v123, v123
	v_add_f32_e32 v117, 1.0, v117
	v_add_f32_e32 v82, 1.0, v82
	v_add_f32_e32 v83, 1.0, v83
	v_rcp_f32_e32 v124, v124
	v_add_f32_e32 v84, 1.0, v84
	v_add_f32_e32 v85, 1.0, v85
	v_pk_mul_f32 v[110:111], v[106:107], v[110:111]
	v_rcp_f32_e32 v125, v125
	v_pk_mul_f32 v[112:113], v[108:109], v[112:113]
	v_pk_mul_f32 v[78:79], v[74:75], v[78:79]
	v_pk_mul_f32 v[80:81], v[76:77], v[80:81]
	v_rcp_f32_e32 v90, v90
	v_mul_f32_e32 v106, 0xbfb8aa3b, v106
	v_mul_f32_e32 v107, 0xbfb8aa3b, v107
	v_rcp_f32_e32 v91, v91
	v_mul_f32_e32 v108, 0xbfb8aa3b, v108
	v_mul_f32_e32 v109, 0xbfb8aa3b, v109
	v_rcp_f32_e32 v92, v92
	v_mul_f32_e32 v74, 0xbfb8aa3b, v74
	v_mul_f32_e32 v75, 0xbfb8aa3b, v75
	v_rcp_f32_e32 v93, v93
	v_mul_f32_e32 v76, 0xbfb8aa3b, v76
	v_mul_f32_e32 v77, 0xbfb8aa3b, v77
	v_exp_f32_e32 v106, v106
	v_pk_mul_f32 v[126:127], v[126:127], v[122:123]
	v_pk_mul_f32 v[128:129], v[128:129], v[124:125]
	v_exp_f32_e32 v107, v107
	v_pk_mul_f32 v[94:95], v[94:95], v[90:91]
	v_pk_mul_f32 v[96:97], v[96:97], v[92:93]
	v_exp_f32_e32 v108, v108
	v_cvt_pk_bf16_f32 v122, v126, v127
	v_cvt_pk_bf16_f32 v123, v128, v129
	v_exp_f32_e32 v109, v109
	v_cvt_pk_bf16_f32 v124, v94, v95
	v_cvt_pk_bf16_f32 v125, v96, v97
	v_exp_f32_e32 v74, v74
	s_nop 1
	v_permlane32_swap_b32_e32 v122, v124
	v_exp_f32_e32 v75, v75
	v_permlane32_swap_b32_e32 v123, v125
	s_nop 1
	v_exp_f32_e32 v76, v76
	v_permlane16_swap_b32_e32 v122, v124
	v_permlane16_swap_b32_e32 v123, v125
	v_exp_f32_e32 v77, v77
	global_store_dwordx4 v[158:159], v[122:125], off
	v_lshl_add_u64 v[158:159], v[158:159], 0, s[20:21]
	v_rcp_f32_e32 v114, v114
	v_add_f32_e32 v106, 1.0, v106
	v_add_f32_e32 v107, 1.0, v107
	v_add_f32_e32 v108, 1.0, v108
	v_rcp_f32_e32 v115, v115
	v_add_f32_e32 v109, 1.0, v109
	v_add_f32_e32 v74, 1.0, v74
	v_add_f32_e32 v75, 1.0, v75
	v_rcp_f32_e32 v116, v116
	v_add_f32_e32 v76, 1.0, v76
	v_add_f32_e32 v77, 1.0, v77
	v_pk_mul_f32 v[102:103], v[98:99], v[102:103]
	v_rcp_f32_e32 v117, v117
	v_pk_mul_f32 v[104:105], v[100:101], v[104:105]
	v_pk_mul_f32 v[70:71], v[66:67], v[70:71]
	v_pk_mul_f32 v[72:73], v[68:69], v[72:73]
	v_rcp_f32_e32 v82, v82
	v_mul_f32_e32 v98, 0xbfb8aa3b, v98
	v_mul_f32_e32 v99, 0xbfb8aa3b, v99
	v_rcp_f32_e32 v83, v83
	v_mul_f32_e32 v100, 0xbfb8aa3b, v100
	v_mul_f32_e32 v101, 0xbfb8aa3b, v101
	v_rcp_f32_e32 v84, v84
	v_mul_f32_e32 v66, 0xbfb8aa3b, v66
	v_mul_f32_e32 v67, 0xbfb8aa3b, v67
	v_rcp_f32_e32 v85, v85
	v_mul_f32_e32 v68, 0xbfb8aa3b, v68
	v_mul_f32_e32 v69, 0xbfb8aa3b, v69
	v_exp_f32_e32 v98, v98
	v_pk_mul_f32 v[118:119], v[118:119], v[114:115]
	v_pk_mul_f32 v[120:121], v[120:121], v[116:117]
	v_exp_f32_e32 v99, v99
	v_pk_mul_f32 v[86:87], v[86:87], v[82:83]
	v_pk_mul_f32 v[88:89], v[88:89], v[84:85]
	v_exp_f32_e32 v100, v100
	v_cvt_pk_bf16_f32 v114, v118, v119
	v_cvt_pk_bf16_f32 v115, v120, v121
	v_exp_f32_e32 v101, v101
	v_cvt_pk_bf16_f32 v116, v86, v87
	v_cvt_pk_bf16_f32 v117, v88, v89
	v_exp_f32_e32 v66, v66
	s_nop 1
	v_permlane32_swap_b32_e32 v114, v116
	v_exp_f32_e32 v67, v67
	v_permlane32_swap_b32_e32 v115, v117
	s_nop 1
	v_exp_f32_e32 v68, v68
	v_permlane16_swap_b32_e32 v114, v116
	v_permlane16_swap_b32_e32 v115, v117
	v_exp_f32_e32 v69, v69
	global_store_dwordx4 v[158:159], v[114:117], off
	v_lshl_add_u64 v[158:159], v[158:159], 0, s[20:21]
	v_rcp_f32_e32 v106, v106
	v_add_f32_e32 v98, 1.0, v98
	v_add_f32_e32 v99, 1.0, v99
	v_add_f32_e32 v100, 1.0, v100
	v_rcp_f32_e32 v107, v107
	v_add_f32_e32 v101, 1.0, v101
	v_add_f32_e32 v66, 1.0, v66
	v_add_f32_e32 v67, 1.0, v67
	v_rcp_f32_e32 v108, v108
	v_add_f32_e32 v68, 1.0, v68
; DI unsigned pack2(float a, float b) { f32x2 v = {a, b}; return __builtin_bit_cast(unsigned, __builtin_convertvector(v, hwbf16x2)); }
; template <int EPI>
; DI void gemm8_epilogue(const GemmArgs& g, f32x4 (&acc)[2][2][4][2], const int brow, const int bcol, const int wr, const int wc, const int fr, const int fq) {
;     ...
;       if constexpr (EPI == EPI_SWIGLU) {
;         bf16_t* H = (bf16_t*)g.out0;
;         const int hc = (cb >> 1) + fq * 4;
; #pragma unroll
;         for (int m = 0; m < 4; ++m) {
;           float v[4];
; #pragma unroll
;           for (int j = 0; j < 4; ++j) { const float gt = acc[ai][bj][m][0][j], up = acc[ai][bj][m][1][j]; v[j] = gt * up * __builtin_amdgcn_rcpf(1.f + __expf(-gt)); }
;           u32x2 o; o.x = pack2(v[0], v[1]); o.y = pack2(v[2], v[3]);
;           *(u32x2*)&H[(size_t)(r0 + m * 16) * DFF + hc] = o;
;         }
	v_add_f32_e32 v69, 1.0, v69
	v_pk_mul_f32 v[62:63], v[58:59], v[62:63]
	v_rcp_f32_e32 v109, v109
	v_pk_mul_f32 v[64:65], v[60:61], v[64:65]
	v_pk_mul_f32 v[30:31], v[26:27], v[30:31]
	v_pk_mul_f32 v[32:33], v[28:29], v[32:33]
	v_rcp_f32_e32 v74, v74
	v_mul_f32_e32 v58, 0xbfb8aa3b, v58
	v_mul_f32_e32 v59, 0xbfb8aa3b, v59
	v_rcp_f32_e32 v75, v75
	v_mul_f32_e32 v60, 0xbfb8aa3b, v60
	v_mul_f32_e32 v61, 0xbfb8aa3b, v61
	v_rcp_f32_e32 v76, v76
	v_mul_f32_e32 v26, 0xbfb8aa3b, v26
	v_mul_f32_e32 v27, 0xbfb8aa3b, v27
	v_rcp_f32_e32 v77, v77
	v_mul_f32_e32 v28, 0xbfb8aa3b, v28
	v_mul_f32_e32 v29, 0xbfb8aa3b, v29
	v_exp_f32_e32 v58, v58
	v_pk_mul_f32 v[110:111], v[110:111], v[106:107]
	v_pk_mul_f32 v[112:113], v[112:113], v[108:109]
	v_exp_f32_e32 v59, v59
	v_pk_mul_f32 v[78:79], v[78:79], v[74:75]
	v_pk_mul_f32 v[80:81], v[80:81], v[76:77]
	v_exp_f32_e32 v60, v60
	v_cvt_pk_bf16_f32 v106, v110, v111
	v_cvt_pk_bf16_f32 v107, v112, v113
	v_exp_f32_e32 v61, v61
	v_cvt_pk_bf16_f32 v108, v78, v79
	v_cvt_pk_bf16_f32 v109, v80, v81
	v_exp_f32_e32 v26, v26
	s_nop 1
	v_permlane32_swap_b32_e32 v106, v108
	v_exp_f32_e32 v27, v27
	v_permlane32_swap_b32_e32 v107, v109
	s_nop 1
	v_exp_f32_e32 v28, v28
	v_permlane16_swap_b32_e32 v106, v108
	v_permlane16_swap_b32_e32 v107, v109
	v_exp_f32_e32 v29, v29
	global_store_dwordx4 v[158:159], v[106:109], off
	v_lshl_add_u64 v[158:159], v[158:159], 0, s[20:21]
	v_rcp_f32_e32 v98, v98
	v_add_f32_e32 v58, 1.0, v58
	v_add_f32_e32 v59, 1.0, v59
	v_add_f32_e32 v60, 1.0, v60
	v_rcp_f32_e32 v99, v99
	v_add_f32_e32 v61, 1.0, v61
	v_add_f32_e32 v26, 1.0, v26
	v_add_f32_e32 v27, 1.0, v27
	v_rcp_f32_e32 v100, v100
	v_add_f32_e32 v28, 1.0, v28
	v_add_f32_e32 v29, 1.0, v29
	v_pk_mul_f32 v[54:55], v[50:51], v[54:55]
	v_rcp_f32_e32 v101, v101
	v_pk_mul_f32 v[56:57], v[52:53], v[56:57]
	v_pk_mul_f32 v[22:23], v[18:19], v[22:23]
	v_pk_mul_f32 v[24:25], v[20:21], v[24:25]
	v_rcp_f32_e32 v66, v66
	v_mul_f32_e32 v50, 0xbfb8aa3b, v50
	v_mul_f32_e32 v51, 0xbfb8aa3b, v51
	v_rcp_f32_e32 v67, v67
	v_mul_f32_e32 v52, 0xbfb8aa3b, v52
	v_mul_f32_e32 v53, 0xbfb8aa3b, v53
	v_rcp_f32_e32 v68, v68
	v_mul_f32_e32 v18, 0xbfb8aa3b, v18
	v_mul_f32_e32 v19, 0xbfb8aa3b, v19
	v_rcp_f32_e32 v69, v69
	v_mul_f32_e32 v20, 0xbfb8aa3b, v20
	v_mul_f32_e32 v21, 0xbfb8aa3b, v21
	v_exp_f32_e32 v50, v50
	v_pk_mul_f32 v[102:103], v[102:103], v[98:99]
	v_pk_mul_f32 v[104:105], v[104:105], v[100:101]
	v_exp_f32_e32 v51, v51
	v_pk_mul_f32 v[70:71], v[70:71], v[66:67]
	v_pk_mul_f32 v[72:73], v[72:73], v[68:69]
	v_exp_f32_e32 v52, v52
	v_cvt_pk_bf16_f32 v98, v102, v103
	v_cvt_pk_bf16_f32 v99, v104, v105
	v_exp_f32_e32 v53, v53
	v_cvt_pk_bf16_f32 v100, v70, v71
	v_cvt_pk_bf16_f32 v101, v72, v73
	v_exp_f32_e32 v18, v18
	s_nop 1
	v_permlane32_swap_b32_e32 v98, v100
	v_exp_f32_e32 v19, v19
	v_permlane32_swap_b32_e32 v99, v101
	s_nop 1
	v_exp_f32_e32 v20, v20
	v_permlane16_swap_b32_e32 v98, v100
	v_permlane16_swap_b32_e32 v99, v101
	v_exp_f32_e32 v21, v21
	global_store_dwordx4 v[158:159], v[98:101], off
	v_lshl_add_u64 v[158:159], v[158:159], 0, s[34:35]
	v_rcp_f32_e32 v58, v58
	v_add_f32_e32 v50, 1.0, v50
	v_add_f32_e32 v51, 1.0, v51
	v_add_f32_e32 v52, 1.0, v52
	v_rcp_f32_e32 v59, v59
	v_add_f32_e32 v53, 1.0, v53
	v_add_f32_e32 v18, 1.0, v18
	v_add_f32_e32 v19, 1.0, v19
	v_rcp_f32_e32 v60, v60
	v_add_f32_e32 v20, 1.0, v20
	v_add_f32_e32 v21, 1.0, v21
	v_pk_mul_f32 v[46:47], v[42:43], v[46:47]
	v_rcp_f32_e32 v61, v61
	v_pk_mul_f32 v[48:49], v[44:45], v[48:49]
	v_pk_mul_f32 v[14:15], v[10:11], v[14:15]
	v_pk_mul_f32 v[16:17], v[12:13], v[16:17]
	v_rcp_f32_e32 v26, v26
	v_mul_f32_e32 v42, 0xbfb8aa3b, v42
	v_mul_f32_e32 v43, 0xbfb8aa3b, v43
	v_rcp_f32_e32 v27, v27
	v_mul_f32_e32 v44, 0xbfb8aa3b, v44
	v_mul_f32_e32 v45, 0xbfb8aa3b, v45
	v_rcp_f32_e32 v28, v28
	v_mul_f32_e32 v10, 0xbfb8aa3b, v10
	v_mul_f32_e32 v11, 0xbfb8aa3b, v11
	v_rcp_f32_e32 v29, v29
	v_mul_f32_e32 v12, 0xbfb8aa3b, v12
	v_mul_f32_e32 v13, 0xbfb8aa3b, v13
	v_exp_f32_e32 v42, v42
	v_pk_mul_f32 v[62:63], v[62:63], v[58:59]
	v_pk_mul_f32 v[64:65], v[64:65], v[60:61]
	v_exp_f32_e32 v43, v43
; DI unsigned pack2(float a, float b) { f32x2 v = {a, b}; return __builtin_bit_cast(unsigned, __builtin_convertvector(v, hwbf16x2)); }
; template <int EPI>
; DI void gemm8_epilogue(const GemmArgs& g, f32x4 (&acc)[2][2][4][2], const int brow, const int bcol, const int wr, const int wc, const int fr, const int fq) {
;     ...
;       if constexpr (EPI == EPI_SWIGLU) {
;         bf16_t* H = (bf16_t*)g.out0;
;         const int hc = (cb >> 1) + fq * 4;
; #pragma unroll
;         for (int m = 0; m < 4; ++m) {
;           float v[4];
; #pragma unroll
;           for (int j = 0; j < 4; ++j) { const float gt = acc[ai][bj][m][0][j], up = acc[ai][bj][m][1][j]; v[j] = gt * up * __builtin_amdgcn_rcpf(1.f + __expf(-gt)); }
;           u32x2 o; o.x = pack2(v[0], v[1]); o.y = pack2(v[2], v[3]);
;           *(u32x2*)&H[(size_t)(r0 + m * 16) * DFF + hc] = o;
;         }
	v_pk_mul_f32 v[30:31], v[30:31], v[26:27]
	v_pk_mul_f32 v[32:33], v[32:33], v[28:29]
	v_exp_f32_e32 v44, v44
	v_cvt_pk_bf16_f32 v58, v62, v63
	v_cvt_pk_bf16_f32 v59, v64, v65
	v_exp_f32_e32 v45, v45
	v_cvt_pk_bf16_f32 v60, v30, v31
	v_cvt_pk_bf16_f32 v61, v32, v33
	v_exp_f32_e32 v10, v10
	s_nop 1
	v_permlane32_swap_b32_e32 v58, v60
	v_exp_f32_e32 v11, v11
	v_permlane32_swap_b32_e32 v59, v61
	s_nop 1
	v_exp_f32_e32 v12, v12
	v_permlane16_swap_b32_e32 v58, v60
	v_permlane16_swap_b32_e32 v59, v61
	v_exp_f32_e32 v13, v13
	global_store_dwordx4 v[158:159], v[58:61], off
	v_lshl_add_u64 v[158:159], v[158:159], 0, s[20:21]
	v_rcp_f32_e32 v50, v50
	v_add_f32_e32 v42, 1.0, v42
	v_add_f32_e32 v43, 1.0, v43
	v_add_f32_e32 v44, 1.0, v44
	v_rcp_f32_e32 v51, v51
	v_add_f32_e32 v45, 1.0, v45
	v_add_f32_e32 v10, 1.0, v10
	v_add_f32_e32 v11, 1.0, v11
	v_rcp_f32_e32 v52, v52
	v_add_f32_e32 v12, 1.0, v12
	v_add_f32_e32 v13, 1.0, v13
	v_pk_mul_f32 v[38:39], v[34:35], v[38:39]
	v_rcp_f32_e32 v53, v53
	v_pk_mul_f32 v[40:41], v[36:37], v[40:41]
	v_pk_mul_f32 v[6:7], v[2:3], v[6:7]
	v_pk_mul_f32 v[8:9], v[4:5], v[8:9]
	v_rcp_f32_e32 v18, v18
	v_mul_f32_e32 v34, 0xbfb8aa3b, v34
	v_mul_f32_e32 v35, 0xbfb8aa3b, v35
	v_rcp_f32_e32 v19, v19
	v_mul_f32_e32 v36, 0xbfb8aa3b, v36
	v_mul_f32_e32 v37, 0xbfb8aa3b, v37
	v_rcp_f32_e32 v20, v20
	v_mul_f32_e32 v2, 0xbfb8aa3b, v2
	v_mul_f32_e32 v3, 0xbfb8aa3b, v3
	v_rcp_f32_e32 v21, v21
	v_mul_f32_e32 v4, 0xbfb8aa3b, v4
	v_mul_f32_e32 v5, 0xbfb8aa3b, v5
	v_exp_f32_e32 v34, v34
	v_pk_mul_f32 v[54:55], v[54:55], v[50:51]
	v_pk_mul_f32 v[56:57], v[56:57], v[52:53]
	v_exp_f32_e32 v35, v35
	v_pk_mul_f32 v[22:23], v[22:23], v[18:19]
	v_pk_mul_f32 v[24:25], v[24:25], v[20:21]
	v_exp_f32_e32 v36, v36
	v_cvt_pk_bf16_f32 v50, v54, v55
	v_cvt_pk_bf16_f32 v51, v56, v57
	v_exp_f32_e32 v37, v37
	v_cvt_pk_bf16_f32 v52, v22, v23
	v_cvt_pk_bf16_f32 v53, v24, v25
	v_exp_f32_e32 v2, v2
	s_nop 1
	v_permlane32_swap_b32_e32 v50, v52
	v_exp_f32_e32 v3, v3
	v_permlane32_swap_b32_e32 v51, v53
	s_nop 1
	v_exp_f32_e32 v4, v4
	v_permlane16_swap_b32_e32 v50, v52
	v_permlane16_swap_b32_e32 v51, v53
	v_exp_f32_e32 v5, v5
	global_store_dwordx4 v[158:159], v[50:53], off
	v_lshl_add_u64 v[158:159], v[158:159], 0, s[20:21]
	v_rcp_f32_e32 v42, v42
	v_add_f32_e32 v34, 1.0, v34
	v_rcp_f32_e32 v43, v43
	v_add_f32_e32 v35, 1.0, v35
	v_rcp_f32_e32 v44, v44
	v_add_f32_e32 v36, 1.0, v36
	v_rcp_f32_e32 v45, v45
	v_add_f32_e32 v37, 1.0, v37
	v_rcp_f32_e32 v10, v10
	v_add_f32_e32 v2, 1.0, v2
	v_rcp_f32_e32 v11, v11
	v_add_f32_e32 v3, 1.0, v3
	v_rcp_f32_e32 v12, v12
	v_add_f32_e32 v4, 1.0, v4
	v_rcp_f32_e32 v13, v13
	v_add_f32_e32 v5, 1.0, v5
	v_rcp_f32_e32 v34, v34
	v_pk_mul_f32 v[46:47], v[46:47], v[42:43]
	v_pk_mul_f32 v[48:49], v[48:49], v[44:45]
	v_rcp_f32_e32 v35, v35
	v_pk_mul_f32 v[14:15], v[14:15], v[10:11]
	v_pk_mul_f32 v[16:17], v[16:17], v[12:13]
	v_rcp_f32_e32 v36, v36
	v_cvt_pk_bf16_f32 v42, v46, v47
	v_cvt_pk_bf16_f32 v43, v48, v49
	v_rcp_f32_e32 v37, v37
	v_cvt_pk_bf16_f32 v44, v14, v15
	v_cvt_pk_bf16_f32 v45, v16, v17
	v_rcp_f32_e32 v2, v2
	s_nop 1
	v_permlane32_swap_b32_e32 v42, v44
	v_rcp_f32_e32 v3, v3
	v_permlane32_swap_b32_e32 v43, v45
	s_nop 1
	v_rcp_f32_e32 v4, v4
	v_permlane16_swap_b32_e32 v42, v44
	v_permlane16_swap_b32_e32 v43, v45
	v_rcp_f32_e32 v5, v5
	global_store_dwordx4 v[158:159], v[42:45], off
	v_lshl_add_u64 v[158:159], v[158:159], 0, s[20:21]
	v_pk_mul_f32 v[38:39], v[38:39], v[34:35]
	v_pk_mul_f32 v[40:41], v[40:41], v[36:37]
	v_pk_mul_f32 v[6:7], v[6:7], v[2:3]
	v_pk_mul_f32 v[8:9], v[8:9], v[4:5]
	v_cvt_pk_bf16_f32 v34, v38, v39
	v_cvt_pk_bf16_f32 v35, v40, v41
	v_cvt_pk_bf16_f32 v36, v6, v7
	v_cvt_pk_bf16_f32 v37, v8, v9
	s_nop 1
	v_permlane32_swap_b32_e32 v34, v36
	v_permlane32_swap_b32_e32 v35, v37
	s_nop 1
	v_permlane16_swap_b32_e32 v34, v36
	v_permlane16_swap_b32_e32 v35, v37
	global_store_dwordx4 v[158:159], v[34:37], off
	s_mov_b64 s[34:35], -1
	s_andn2_b64 vcc, exec, s[46:47]
	s_cbranch_vccnz .LBB0_288
	s_andn2_b64 vcc, exec, s[0:1]
	s_cbranch_vccnz .LBB0_287
	s_barrier
	s_branch .LBB0_287
